# P4 item order: each wave does its two DeltaNet items before its two HGRN2 items (DN states written last by the scan, fresher in the infinity cache); on p4pipe
# speedup vs baseline: 1.0011x; 1.0011x over previous
; #define GAS __attribute__((address_space(1)))
; __device__ __forceinline__ unsigned long long rt() { return __builtin_amdgcn_s_memrealtime(); }
; __device__ __forceinline__ void p4_load_a(P4Pre& P, const P4Ptr& p, int lane) {
;     const int r = lane & 15, g = lane >> 4, t = 16 * p.mt + r;
; #pragma unroll
;     for (int kb = 0; kb < 4; ++kb) P.ya[kb] = *(const GAS bf16x8*)(p.region + (size_t)((p.mt * 4 + kb) * 64 + lane) * 8);
; #pragma unroll
;     for (int vt = 0; vt < 4; ++vt)
; #pragma unroll
;         for (int kb = 0; kb < 4; ++kb) P.x[vt][kb] = *(const GAS bf16x8*)(p.sn + (size_t)((vt * 4 + kb) * 64 + lane) * 8);
; #pragma unroll
;     for (int vt = 0; vt < 8; ++vt) { P.ol[vt] = *(const GAS u64_t*)(p.oloc + (size_t)((vt * 4 + p.mt) * 64 + lane) * 4); P.gt8[vt] = *(const GAS u64_t*)(p.region + 24576 + t * 128 + 16 * vt + 4 * g); }
; }
; __device__ __forceinline__ void p4_run(int gw, int NGW, const bf16_t* HGR, const bf16_t* DNR, const bf16_t* OLH, const bf16_t* OLD, const bf16_t* BNB, const float* hg_nw, const float* dn_nw, bf16_t* OAB, int lane) {
;     const int r = lane & 15, g = lane >> 4;
;     P4Pre P; P4Ptr p = p4_ptrs(gw, HGR, DNR, OLH, OLD, BNB, hg_nw, dn_nw);
;     if (gw < 8192) p4_load_a(P, p, lane);
; __global__ void __launch_bounds__(NWAVES * 64, 2) fwd(Args args) {
;     ...
;     if (IN(4)) {
;         const unsigned long long amp_t0_4 = (PROBE_AMP == 4) ? rt() : 0ull;
;         _Pragma("unroll 1") for (int rep_ = 0; rep_ < ((PROBE == 4) ? 2 : 1); ++rep_) {
;         const int gw = (int)blockIdx.x * NWAVES + wave, NGW = G * NWAVES;
;         p4_run(gw, NGW, HGR, DNR, OLH, OLD, BNB, args.in[4], args.in[7], OAB, lane);
.LBB0_890:
	s_add_u32 s10, s60, 0xa004000
	s_addc_u32 s11, s61, 0
	s_add_u32 s8, s60, 0xe000000
	s_addc_u32 s9, s61, 0
	s_cmp_lt_i32 s56, 5
	s_cselect_b64 s[0:1], -1, 0
	s_cmp_gt_i32 s57, 4
	s_cselect_b64 s[4:5], -1, 0
	s_and_b64 s[0:1], s[0:1], s[4:5]
	s_andn2_b64 vcc, exec, s[0:1]
	s_cbranch_vccnz .LBB0_946
	s_and_b32 s4, s72, 56
	s_and_b32 s0, s73, 7
	s_or_b32 s4, s4, s0
	s_lshl_b32 s4, s4, 6
	s_lshr_b32 s0, s2, 6
	s_lshl_b32 s0, s0, 3
	s_add_i32 s4, s4, s0
	s_add_i32 s4, s4, s48
	s_cmpk_gt_i32 s4, 0x1fff
	s_cbranch_scc1 .LBB0_896
	s_or_b32 s4, s4, 0x1000
	s_waitcnt vmcnt(0)
	s_bfe_u32 s38, s66, 0x20006
	v_lshlrev_b32_e32 v210, 4, v234
	v_and_b32_e32 v211, 15, v234
	v_lshrrev_b32_e32 v212, 4, v234
	v_lshlrev_b32_e32 v213, 8, v211
	v_lshl_or_b32 v213, v212, 3, v213
	v_and_b32_e32 v214, 1, v212
	v_lshlrev_b32_e32 v214, 5, v214
	v_lshrrev_b32_e32 v215, 1, v212
	v_lshl_or_b32 v214, v215, 4, v214
	v_lshl_or_b32 v214, v211, 11, v214
	v_lshlrev_b32_e32 v215, 4, v212
	v_lshlrev_b32_e32 v216, 3, v234
	v_xor_b32_e32 v217, 16, v234
	v_lshlrev_b32_e32 v217, 2, v217
	v_xor_b32_e32 v218, 32, v234
	v_lshlrev_b32_e32 v218, 2, v218
	v_mov_b32_e32 v219, 0x358637bd
	s_bfe_u32 s36, s4, 0xa0002
	s_bfe_u32 s47, s4, 0x20002
	s_cmpk_lt_u32 s4, 0x1000
	s_cselect_b32 s6, s26, s62
	s_cselect_b32 s7, s27, s63
	s_lshl_b32 s3, s36, 16
	s_add_u32 s28, s6, s3
	s_addc_u32 s29, s7, 0
	s_add_u32 s40, s28, 0x4000
	s_addc_u32 s41, s29, 0
	s_lshl_b32 s3, s36, 15
	s_add_u32 s42, s64, s3
	s_addc_u32 s43, s65, 0
	s_cmpk_lt_u32 s4, 0x1000
	s_cselect_b32 s40, s40, s42
	s_cselect_b32 s41, s41, s43
	s_add_u32 s42, s60, 0xf000000
	s_addc_u32 s43, s61, 0
	s_cmpk_lt_u32 s4, 0x1000
	s_cselect_b32 s42, s8, s42
	s_cselect_b32 s43, s9, s43
	s_lshl_b32 s3, s36, 14
	s_add_u32 s42, s42, s3
	s_addc_u32 s43, s43, 0
	s_lshl_b32 s3, s38, 9
	s_add_u32 s42, s42, s3
	s_addc_u32 s43, s43, 0
	s_lshl_b32 s3, s47, 9
	s_add_u32 s44, s24, s3
	s_addc_u32 s45, s25, 0
	s_cmpk_lt_u32 s4, 0x1000
	s_cselect_b32 s44, s44, s30
	s_cselect_b32 s45, s45, s31
	s_lshl_b32 s3, s38, 12
	s_add_u32 s50, s28, s3
	s_addc_u32 s51, s29, 0
	s_add_u32 s18, s50, 0xc000
	s_addc_u32 s19, s51, 0
	s_lshr_b32 s3, s36, 2
	s_lshl_b32 s3, s3, 2
	s_or_b32 s3, s3, s38
	s_lshl_b32 s3, s3, 16
	s_add_u32 s68, s10, s3
	s_addc_u32 s69, s11, 0
	s_lshr_b32 s3, s4, 12
	s_lshl_b32 s3, s3, 10
	s_lshl_b32 s33, s47, 8
	s_or_b32 s3, s3, s33
	s_add_u32 s68, s68, s3
	s_addc_u32 s69, s69, 0
	s_mov_b64 s[74:75], s[40:41]
	global_load_dwordx4 v[2:5], v210, s[50:51]
	global_load_dwordx4 v[6:9], v210, s[50:51] offset:1024
	global_load_dwordx4 v[10:13], v210, s[50:51] offset:2048
	global_load_dwordx4 v[14:17], v210, s[50:51] offset:3072
	global_load_dwordx4 v[22:25], v210, s[40:41] offset:1024
	global_load_dwordx4 v[26:29], v210, s[40:41] offset:2048
	global_load_dwordx4 v[30:33], v210, s[40:41] offset:3072
	s_add_u32 s40, s40, 0x1000
	s_addc_u32 s41, s41, 0
	global_load_dwordx4 v[38:41], v210, s[40:41] offset:1024
	global_load_dwordx4 v[42:45], v210, s[40:41] offset:2048
	global_load_dwordx4 v[46:49], v210, s[40:41] offset:3072
	s_add_u32 s40, s40, 0x1000
	s_addc_u32 s41, s41, 0
	global_load_dwordx4 v[54:57], v210, s[40:41] offset:1024
	global_load_dwordx4 v[58:61], v210, s[40:41] offset:2048
	global_load_dwordx4 v[62:65], v210, s[40:41] offset:3072
	s_add_u32 s40, s40, 0x1000
	s_addc_u32 s41, s41, 0
	global_load_dwordx4 v[70:73], v210, s[40:41] offset:1024
	global_load_dwordx4 v[74:77], v210, s[40:41] offset:2048
	global_load_dwordx4 v[78:81], v210, s[40:41] offset:3072
	s_add_u32 s40, s40, 0x1000
	s_addc_u32 s41, s41, 0
	global_load_dwordx4 v[86:89], v210, s[40:41] offset:1024
	global_load_dwordx4 v[90:93], v210, s[40:41] offset:2048
	global_load_dwordx4 v[94:97], v210, s[40:41] offset:3072
	s_add_u32 s40, s40, 0x1000
	s_addc_u32 s41, s41, 0
	global_load_dwordx4 v[102:105], v210, s[40:41] offset:1024
	global_load_dwordx4 v[106:109], v210, s[40:41] offset:2048
	global_load_dwordx4 v[110:113], v210, s[40:41] offset:3072
	s_add_u32 s40, s40, 0x1000
	s_addc_u32 s41, s41, 0
	global_load_dwordx4 v[118:121], v210, s[40:41] offset:1024
	global_load_dwordx4 v[122:125], v210, s[40:41] offset:2048
	global_load_dwordx4 v[126:129], v210, s[40:41] offset:3072
	s_add_u32 s40, s40, 0x1000
	s_addc_u32 s41, s41, 0
	global_load_dwordx4 v[134:137], v210, s[40:41] offset:1024
	global_load_dwordx4 v[138:141], v210, s[40:41] offset:2048
	global_load_dwordx4 v[142:145], v210, s[40:41] offset:3072
	global_load_dwordx2 v[146:147], v216, s[42:43]
	global_load_dwordx2 v[148:149], v216, s[42:43] offset:2048
	s_add_u32 s42, s42, 0x1000
	s_addc_u32 s43, s43, 0
	global_load_dwordx2 v[150:151], v216, s[42:43]
	global_load_dwordx2 v[152:153], v216, s[42:43] offset:2048
	s_add_u32 s42, s42, 0x1000
	s_addc_u32 s43, s43, 0
	global_load_dwordx2 v[154:155], v216, s[42:43]
	global_load_dwordx2 v[156:157], v216, s[42:43] offset:2048
	s_add_u32 s42, s42, 0x1000
	s_addc_u32 s43, s43, 0
	global_load_dwordx2 v[158:159], v216, s[42:43]
	global_load_dwordx2 v[160:161], v216, s[42:43] offset:2048
; #define GAS __attribute__((address_space(1)))
; #define MFMA16(a, b, c) __builtin_amdgcn_mfma_f32_16x16x32_bf16((a), (b), (c), 0, 0, 0)
; __device__ __forceinline__ void p4_run(int gw, int NGW, const bf16_t* HGR, const bf16_t* DNR, const bf16_t* OLH, const bf16_t* OLD, const bf16_t* BNB, const float* hg_nw, const float* dn_nw, bf16_t* OAB, int lane) {
;     ...
;     for (int it = gw; it < 8192; it += NGW) {
;         asm volatile("" ::: "memory");
;         f32x4 o[8]; float ss = 0.f; u64_t gcur[8];
; #pragma unroll
;         for (int vt = 0; vt < 8; ++vt) gcur[vt] = P.gt8[vt];
; #pragma unroll
;         for (int vt = 0; vt < 4; ++vt) { f32x4 acc = unpack4(P.ol[vt]);
; #pragma unroll
;             for (int kb = 0; kb < 4; ++kb) acc = MFMA16(P.x[vt][kb], P.ya[kb], acc);
;             o[vt] = acc; ss += (acc[0] * acc[0] + acc[1] * acc[1]) + (acc[2] * acc[2] + acc[3] * acc[3]); }
;         asm volatile("" ::: "memory");
; #pragma unroll
;         for (int vt = 0; vt < 4; ++vt)
; #pragma unroll
;             for (int kb = 0; kb < 4; ++kb) P.x[vt][kb] = *(const GAS bf16x8*)(p.sn + (size_t)(((vt + 4) * 4 + kb) * 64 + lane) * 8);
;         f32x4 w8[8];
; #pragma unroll
;         for (int vt = 0; vt < 8; ++vt) w8[vt] = *(const GAS f32x4*)(p.nw + 16 * vt + 4 * g);
;         asm volatile("" ::: "memory");
; #pragma unroll
;         for (int vt = 0; vt < 4; ++vt) { f32x4 acc = unpack4(P.ol[vt + 4]);
; #pragma unroll
;             for (int kb = 0; kb < 4; ++kb) acc = MFMA16(P.x[vt][kb], P.ya[kb], acc);
;             o[vt + 4] = acc; ss += (acc[0] * acc[0] + acc[1] * acc[1]) + (acc[2] * acc[2] + acc[3] * acc[3]); }
;         const int t = 16 * p.mt + r;
;         bf16_t* orow2 = OAB + (size_t)(p.rb * 4 + p.mt) * 32768 + r * 1024 + p.br * 512 + p.h * 128 + 16 * (g & 1) + 8 * (g >> 1);
;         asm volatile("" :: "v"(o[4][0]), "v"(o[5][0]), "v"(o[6][0]), "v"(o[7][0]) : "memory");
;         if (it + NGW < 8192) { p = p4_ptrs(it + NGW, HGR, DNR, OLH, OLD, BNB, hg_nw, dn_nw); p4_load_a(P, p, lane); }
;         asm volatile("" ::: "memory");
;         ss += __shfl_xor(ss, 16); ss += __shfl_xor(ss, 32);
;         const float rstd = rsqrtf(ss * (1.f / 128.f) + RMS_EPS);
.Lp4n_item:
	global_load_dwordx4 v[18:21], v210, s[74:75]
	s_add_u32 s74, s74, 0x1000
	s_addc_u32 s75, s75, 0
	global_load_dwordx4 v[34:37], v210, s[74:75]
	s_add_u32 s74, s74, 0x1000
	s_addc_u32 s75, s75, 0
	global_load_dwordx4 v[50:53], v210, s[74:75]
	s_add_u32 s74, s74, 0x1000
	s_addc_u32 s75, s75, 0
	global_load_dwordx4 v[66:69], v210, s[74:75]
	s_add_u32 s74, s74, 0x1000
	s_addc_u32 s75, s75, 0
	global_load_dwordx4 v[82:85], v210, s[74:75]
	s_add_u32 s74, s74, 0x1000
	s_addc_u32 s75, s75, 0
	global_load_dwordx4 v[98:101], v210, s[74:75]
	s_add_u32 s74, s74, 0x1000
	s_addc_u32 s75, s75, 0
	global_load_dwordx4 v[114:117], v210, s[74:75]
	s_add_u32 s74, s74, 0x1000
	s_addc_u32 s75, s75, 0
	global_load_dwordx4 v[130:133], v210, s[74:75]
	global_load_dwordx2 v[162:163], v213, s[18:19]
	global_load_dwordx2 v[164:165], v213, s[18:19] offset:32
	global_load_dwordx2 v[166:167], v213, s[18:19] offset:64
	global_load_dwordx2 v[168:169], v213, s[18:19] offset:96
	global_load_dwordx2 v[170:171], v213, s[18:19] offset:128
	global_load_dwordx2 v[172:173], v213, s[18:19] offset:160
	global_load_dwordx2 v[174:175], v213, s[18:19] offset:192
	global_load_dwordx2 v[176:177], v213, s[18:19] offset:224
	s_waitcnt vmcnt(8)
	v_lshlrev_b32_e32 v178, 16, v146
	v_and_b32_e32 v179, 0xffff0000, v146
	v_lshlrev_b32_e32 v180, 16, v147
	v_and_b32_e32 v181, 0xffff0000, v147
	v_lshlrev_b32_e32 v182, 16, v148
	v_and_b32_e32 v183, 0xffff0000, v148
	v_lshlrev_b32_e32 v184, 16, v149
	v_and_b32_e32 v185, 0xffff0000, v149
	v_lshlrev_b32_e32 v186, 16, v150
	v_and_b32_e32 v187, 0xffff0000, v150
	v_lshlrev_b32_e32 v188, 16, v151
	v_and_b32_e32 v189, 0xffff0000, v151
	v_lshlrev_b32_e32 v190, 16, v152
	v_and_b32_e32 v191, 0xffff0000, v152
	v_lshlrev_b32_e32 v192, 16, v153
	v_and_b32_e32 v193, 0xffff0000, v153
	v_lshlrev_b32_e32 v194, 16, v154
	v_and_b32_e32 v195, 0xffff0000, v154
	v_lshlrev_b32_e32 v196, 16, v155
	v_and_b32_e32 v197, 0xffff0000, v155
	v_lshlrev_b32_e32 v198, 16, v156
	v_and_b32_e32 v199, 0xffff0000, v156
	v_lshlrev_b32_e32 v200, 16, v157
	v_and_b32_e32 v201, 0xffff0000, v157
	v_lshlrev_b32_e32 v202, 16, v158
	v_and_b32_e32 v203, 0xffff0000, v158
	v_lshlrev_b32_e32 v204, 16, v159
	v_and_b32_e32 v205, 0xffff0000, v159
	v_lshlrev_b32_e32 v206, 16, v160
	v_and_b32_e32 v207, 0xffff0000, v160
	v_lshlrev_b32_e32 v208, 16, v161
	v_and_b32_e32 v209, 0xffff0000, v161
	s_nop 1
	v_mfma_f32_16x16x32_bf16 v[178:181], v[18:21], v[2:5], v[178:181]
	v_mfma_f32_16x16x32_bf16 v[182:185], v[34:37], v[2:5], v[182:185]
	v_mfma_f32_16x16x32_bf16 v[186:189], v[50:53], v[2:5], v[186:189]
	v_mfma_f32_16x16x32_bf16 v[190:193], v[66:69], v[2:5], v[190:193]
	v_mfma_f32_16x16x32_bf16 v[194:197], v[82:85], v[2:5], v[194:197]
	v_mfma_f32_16x16x32_bf16 v[198:201], v[98:101], v[2:5], v[198:201]
	v_mfma_f32_16x16x32_bf16 v[202:205], v[114:117], v[2:5], v[202:205]
	v_mfma_f32_16x16x32_bf16 v[206:209], v[130:133], v[2:5], v[206:209]
	global_load_dwordx4 v[18:21], v215, s[44:45]
	global_load_dwordx4 v[34:37], v215, s[44:45] offset:64
	global_load_dwordx4 v[50:53], v215, s[44:45] offset:128
	global_load_dwordx4 v[66:69], v215, s[44:45] offset:192
	global_load_dwordx4 v[82:85], v215, s[44:45] offset:256
	global_load_dwordx4 v[98:101], v215, s[44:45] offset:320
	global_load_dwordx4 v[114:117], v215, s[44:45] offset:384
	global_load_dwordx4 v[130:133], v215, s[44:45] offset:448
	v_mfma_f32_16x16x32_bf16 v[178:181], v[22:25], v[6:9], v[178:181]
	v_mfma_f32_16x16x32_bf16 v[182:185], v[38:41], v[6:9], v[182:185]
	v_mfma_f32_16x16x32_bf16 v[186:189], v[54:57], v[6:9], v[186:189]
	v_mfma_f32_16x16x32_bf16 v[190:193], v[70:73], v[6:9], v[190:193]
	v_mfma_f32_16x16x32_bf16 v[194:197], v[86:89], v[6:9], v[194:197]
	v_mfma_f32_16x16x32_bf16 v[198:201], v[102:105], v[6:9], v[198:201]
	v_mfma_f32_16x16x32_bf16 v[202:205], v[118:121], v[6:9], v[202:205]
	v_mfma_f32_16x16x32_bf16 v[206:209], v[134:137], v[6:9], v[206:209]
	v_mfma_f32_16x16x32_bf16 v[178:181], v[26:29], v[10:13], v[178:181]
	v_mfma_f32_16x16x32_bf16 v[182:185], v[42:45], v[10:13], v[182:185]
	v_mfma_f32_16x16x32_bf16 v[186:189], v[58:61], v[10:13], v[186:189]
	v_mfma_f32_16x16x32_bf16 v[190:193], v[74:77], v[10:13], v[190:193]
	v_mfma_f32_16x16x32_bf16 v[194:197], v[90:93], v[10:13], v[194:197]
	v_mfma_f32_16x16x32_bf16 v[198:201], v[106:109], v[10:13], v[198:201]
	v_mfma_f32_16x16x32_bf16 v[202:205], v[122:125], v[10:13], v[202:205]
	v_mfma_f32_16x16x32_bf16 v[206:209], v[138:141], v[10:13], v[206:209]
	v_mfma_f32_16x16x32_bf16 v[178:181], v[30:33], v[14:17], v[178:181]
	v_mfma_f32_16x16x32_bf16 v[182:185], v[46:49], v[14:17], v[182:185]
	v_mfma_f32_16x16x32_bf16 v[186:189], v[62:65], v[14:17], v[186:189]
	v_mfma_f32_16x16x32_bf16 v[190:193], v[78:81], v[14:17], v[190:193]
	v_mfma_f32_16x16x32_bf16 v[194:197], v[94:97], v[14:17], v[194:197]
	v_mfma_f32_16x16x32_bf16 v[198:201], v[110:113], v[14:17], v[198:201]
	v_mfma_f32_16x16x32_bf16 v[202:205], v[126:129], v[14:17], v[202:205]
	v_mfma_f32_16x16x32_bf16 v[206:209], v[142:145], v[14:17], v[206:209]
	s_nop 7
	s_nop 3
	v_mul_f32_e32 v229, v179, v179
	v_mul_f32_e32 v230, v181, v181
	v_fmac_f32_e32 v229, v178, v178
	v_fmac_f32_e32 v230, v180, v180
	v_add_f32_e32 v229, v229, v230
	v_mov_b32_e32 v228, v229
	v_mul_f32_e32 v229, v183, v183
	v_mul_f32_e32 v230, v185, v185
	v_fmac_f32_e32 v229, v182, v182
	v_fmac_f32_e32 v230, v184, v184
	v_add_f32_e32 v229, v229, v230
	v_add_f32_e32 v228, v228, v229
	v_mul_f32_e32 v229, v187, v187
	v_mul_f32_e32 v230, v189, v189
	v_fmac_f32_e32 v229, v186, v186
	v_fmac_f32_e32 v230, v188, v188
	v_add_f32_e32 v229, v229, v230
	v_add_f32_e32 v228, v228, v229
	v_mul_f32_e32 v229, v191, v191
	v_mul_f32_e32 v230, v193, v193
	v_fmac_f32_e32 v229, v190, v190
	v_fmac_f32_e32 v230, v192, v192
	v_add_f32_e32 v229, v229, v230
	v_add_f32_e32 v228, v228, v229
	v_mul_f32_e32 v229, v195, v195
	v_mul_f32_e32 v230, v197, v197
	v_fmac_f32_e32 v229, v194, v194
	v_fmac_f32_e32 v230, v196, v196
	v_add_f32_e32 v229, v229, v230
	v_add_f32_e32 v228, v228, v229
	v_mul_f32_e32 v229, v199, v199
	v_mul_f32_e32 v230, v201, v201
	v_fmac_f32_e32 v229, v198, v198
	v_fmac_f32_e32 v230, v200, v200
	v_add_f32_e32 v229, v229, v230
	v_add_f32_e32 v228, v228, v229
	v_mul_f32_e32 v229, v203, v203
	v_mul_f32_e32 v230, v205, v205
	v_fmac_f32_e32 v229, v202, v202
	v_fmac_f32_e32 v230, v204, v204
	v_add_f32_e32 v229, v229, v230
	v_add_f32_e32 v228, v228, v229
	v_mul_f32_e32 v229, v207, v207
	v_mul_f32_e32 v230, v209, v209
	v_fmac_f32_e32 v229, v206, v206
	v_fmac_f32_e32 v230, v208, v208
	v_add_f32_e32 v229, v229, v230
	v_add_f32_e32 v228, v228, v229
	ds_bpermute_b32 v229, v217, v228
	s_waitcnt lgkmcnt(0)
	v_add_f32_e32 v228, v228, v229
	ds_bpermute_b32 v229, v218, v228
	s_waitcnt lgkmcnt(0)
	v_add_f32_e32 v228, v228, v229
	v_fmamk_f32 v228, v228, 0x3c000000, v219
	v_rsq_f32_e32 v232, v228
	v_mov_b32_e32 v233, 0
	s_bitcmp1_b32 s4, 5
	s_cselect_b32 s35, 0xffffefe0, 32
	s_add_i32 s4, s4, s35
	s_cmp_lt_i32 s4, 0
	s_cbranch_scc1 .Lp4n_last
; #define GAS __attribute__((address_space(1)))
; __device__ __forceinline__ void p4_load_a(P4Pre& P, const P4Ptr& p, int lane) {
;     const int r = lane & 15, g = lane >> 4, t = 16 * p.mt + r;
; #pragma unroll
;     for (int kb = 0; kb < 4; ++kb) P.ya[kb] = *(const GAS bf16x8*)(p.region + (size_t)((p.mt * 4 + kb) * 64 + lane) * 8);
; #pragma unroll
;     for (int vt = 0; vt < 4; ++vt)
; #pragma unroll
;         for (int kb = 0; kb < 4; ++kb) P.x[vt][kb] = *(const GAS bf16x8*)(p.sn + (size_t)((vt * 4 + kb) * 64 + lane) * 8);
; #pragma unroll
;     for (int vt = 0; vt < 8; ++vt) { P.ol[vt] = *(const GAS u64_t*)(p.oloc + (size_t)((vt * 4 + p.mt) * 64 + lane) * 4); P.gt8[vt] = *(const GAS u64_t*)(p.region + 24576 + t * 128 + 16 * vt + 4 * g); }
; }
; __device__ __forceinline__ void p4_run(int gw, int NGW, const bf16_t* HGR, const bf16_t* DNR, const bf16_t* OLH, const bf16_t* OLD, const bf16_t* BNB, const float* hg_nw, const float* dn_nw, bf16_t* OAB, int lane) {
;     ...
;         if (it + NGW < 8192) { p = p4_ptrs(it + NGW, HGR, DNR, OLH, OLD, BNB, hg_nw, dn_nw); p4_load_a(P, p, lane); }
	s_bfe_u32 s36, s4, 0xa0002
	s_bfe_u32 s47, s4, 0x20002
	s_cmpk_lt_u32 s4, 0x1000
	s_cselect_b32 s6, s26, s62
	s_cselect_b32 s7, s27, s63
	s_lshl_b32 s3, s36, 16
	s_add_u32 s28, s6, s3
	s_addc_u32 s29, s7, 0
	s_add_u32 s40, s28, 0x4000
	s_addc_u32 s41, s29, 0
	s_lshl_b32 s3, s36, 15
	s_add_u32 s42, s64, s3
	s_addc_u32 s43, s65, 0
	s_cmpk_lt_u32 s4, 0x1000
	s_cselect_b32 s40, s40, s42
	s_cselect_b32 s41, s41, s43
	s_add_u32 s42, s60, 0xf000000
	s_addc_u32 s43, s61, 0
	s_cmpk_lt_u32 s4, 0x1000
	s_cselect_b32 s42, s8, s42
	s_cselect_b32 s43, s9, s43
	s_lshl_b32 s3, s36, 14
	s_add_u32 s42, s42, s3
	s_addc_u32 s43, s43, 0
	s_lshl_b32 s3, s38, 9
	s_add_u32 s42, s42, s3
	s_addc_u32 s43, s43, 0
	s_lshl_b32 s3, s47, 9
	s_add_u32 s44, s24, s3
	s_addc_u32 s45, s25, 0
	s_cmpk_lt_u32 s4, 0x1000
	s_cselect_b32 s44, s44, s30
	s_cselect_b32 s45, s45, s31
	s_lshl_b32 s3, s38, 12
	s_add_u32 s50, s28, s3
	s_addc_u32 s51, s29, 0
	s_add_u32 s18, s50, 0xc000
	s_addc_u32 s19, s51, 0
	s_lshr_b32 s3, s36, 2
	s_lshl_b32 s3, s3, 2
	s_or_b32 s3, s3, s38
	s_lshl_b32 s3, s3, 16
	s_add_u32 s70, s10, s3
	s_addc_u32 s71, s11, 0
	s_lshr_b32 s3, s4, 12
	s_lshl_b32 s3, s3, 10
	s_lshl_b32 s33, s47, 8
	s_or_b32 s3, s3, s33
	s_add_u32 s70, s70, s3
	s_addc_u32 s71, s71, 0
	s_mov_b64 s[74:75], s[40:41]
	global_load_dwordx4 v[2:5], v210, s[50:51]
	global_load_dwordx4 v[6:9], v210, s[50:51] offset:1024
	global_load_dwordx4 v[10:13], v210, s[50:51] offset:2048
	global_load_dwordx4 v[14:17], v210, s[50:51] offset:3072
	global_load_dwordx4 v[22:25], v210, s[40:41] offset:1024
	global_load_dwordx4 v[26:29], v210, s[40:41] offset:2048
	global_load_dwordx4 v[30:33], v210, s[40:41] offset:3072
	s_add_u32 s40, s40, 0x1000
	s_addc_u32 s41, s41, 0
	global_load_dwordx4 v[38:41], v210, s[40:41] offset:1024
	global_load_dwordx4 v[42:45], v210, s[40:41] offset:2048
	global_load_dwordx4 v[46:49], v210, s[40:41] offset:3072
	s_add_u32 s40, s40, 0x1000
	s_addc_u32 s41, s41, 0
	global_load_dwordx4 v[54:57], v210, s[40:41] offset:1024
	global_load_dwordx4 v[58:61], v210, s[40:41] offset:2048
	global_load_dwordx4 v[62:65], v210, s[40:41] offset:3072
	s_add_u32 s40, s40, 0x1000
	s_addc_u32 s41, s41, 0
	global_load_dwordx4 v[70:73], v210, s[40:41] offset:1024
	global_load_dwordx4 v[74:77], v210, s[40:41] offset:2048
	global_load_dwordx4 v[78:81], v210, s[40:41] offset:3072
	s_add_u32 s40, s40, 0x1000
	s_addc_u32 s41, s41, 0
	global_load_dwordx4 v[86:89], v210, s[40:41] offset:1024
	global_load_dwordx4 v[90:93], v210, s[40:41] offset:2048
	global_load_dwordx4 v[94:97], v210, s[40:41] offset:3072
	s_add_u32 s40, s40, 0x1000
	s_addc_u32 s41, s41, 0
	global_load_dwordx4 v[102:105], v210, s[40:41] offset:1024
	global_load_dwordx4 v[106:109], v210, s[40:41] offset:2048
	global_load_dwordx4 v[110:113], v210, s[40:41] offset:3072
	s_add_u32 s40, s40, 0x1000
	s_addc_u32 s41, s41, 0
	global_load_dwordx4 v[118:121], v210, s[40:41] offset:1024
	global_load_dwordx4 v[122:125], v210, s[40:41] offset:2048
	global_load_dwordx4 v[126:129], v210, s[40:41] offset:3072
	s_add_u32 s40, s40, 0x1000
	s_addc_u32 s41, s41, 0
	global_load_dwordx4 v[134:137], v210, s[40:41] offset:1024
	global_load_dwordx4 v[138:141], v210, s[40:41] offset:2048
	global_load_dwordx4 v[142:145], v210, s[40:41] offset:3072
	global_load_dwordx2 v[146:147], v216, s[42:43]
	global_load_dwordx2 v[148:149], v216, s[42:43] offset:2048
	s_add_u32 s42, s42, 0x1000
	s_addc_u32 s43, s43, 0
	global_load_dwordx2 v[150:151], v216, s[42:43]
	global_load_dwordx2 v[152:153], v216, s[42:43] offset:2048
	s_add_u32 s42, s42, 0x1000
	s_addc_u32 s43, s43, 0
	global_load_dwordx2 v[154:155], v216, s[42:43]
	global_load_dwordx2 v[156:157], v216, s[42:43] offset:2048
	s_add_u32 s42, s42, 0x1000
	s_addc_u32 s43, s43, 0
	global_load_dwordx2 v[158:159], v216, s[42:43]
	global_load_dwordx2 v[160:161], v216, s[42:43] offset:2048
	s_waitcnt vmcnt(36)
	s_branch .Lp4n_tail

; #define GAS __attribute__((address_space(1)))
; __device__ __forceinline__ u64_t pack4(const f32x4 v) { return (u64_t)pk2(v[0], v[1]) | ((u64_t)pk2(v[2], v[3]) << 32); }
; __device__ __forceinline__ void p4_run(int gw, int NGW, const bf16_t* HGR, const bf16_t* DNR, const bf16_t* OLH, const bf16_t* OLD, const bf16_t* BNB, const float* hg_nw, const float* dn_nw, bf16_t* OAB, int lane) {
;     ...
;         ss += __shfl_xor(ss, 16); ss += __shfl_xor(ss, 32);
;         const float rstd = rsqrtf(ss * (1.f / 128.f) + RMS_EPS);
; #pragma unroll
;         for (int p2 = 0; p2 < 4; ++p2) {
;             const u64_t X = pack4(o[2 * p2] * rstd * w8[2 * p2] * unpack4(gcur[2 * p2])), Y = pack4(o[2 * p2 + 1] * rstd * w8[2 * p2 + 1] * unpack4(gcur[2 * p2 + 1]));
;             const auto lo = __builtin_amdgcn_permlane16_swap((unsigned)X, (unsigned)Y, false, false), hi = __builtin_amdgcn_permlane16_swap((unsigned)(X >> 32), (unsigned)(Y >> 32), false, false);
;             *(GAS v4u*)(orow2 + 32 * p2) = (v4u){lo[0], hi[0], lo[1], hi[1]}; }
;     }
.Lp4n_tail:
	v_pk_mul_f32 v[178:179], v[178:179], v[232:233] op_sel_hi:[1,0]
	v_pk_mul_f32 v[180:181], v[180:181], v[232:233] op_sel_hi:[1,0]
	v_lshlrev_b32_e32 v220, 16, v162
	v_and_b32_e32 v221, 0xffff0000, v162
	v_lshlrev_b32_e32 v222, 16, v163
	v_and_b32_e32 v223, 0xffff0000, v163
	v_pk_mul_f32 v[178:179], v[18:19], v[178:179]
	v_pk_mul_f32 v[180:181], v[20:21], v[180:181]
	v_pk_mul_f32 v[178:179], v[178:179], v[220:221]
	v_pk_mul_f32 v[180:181], v[180:181], v[222:223]
	v_cvt_pk_bf16_f32 v224, v178, v179
	v_cvt_pk_bf16_f32 v225, v180, v181
	v_pk_mul_f32 v[182:183], v[182:183], v[232:233] op_sel_hi:[1,0]
	v_pk_mul_f32 v[184:185], v[184:185], v[232:233] op_sel_hi:[1,0]
	v_lshlrev_b32_e32 v220, 16, v164
	v_and_b32_e32 v221, 0xffff0000, v164
	v_lshlrev_b32_e32 v222, 16, v165
	v_and_b32_e32 v223, 0xffff0000, v165
	v_pk_mul_f32 v[182:183], v[34:35], v[182:183]
	v_pk_mul_f32 v[184:185], v[36:37], v[184:185]
	v_pk_mul_f32 v[182:183], v[182:183], v[220:221]
	v_pk_mul_f32 v[184:185], v[184:185], v[222:223]
	v_cvt_pk_bf16_f32 v226, v182, v183
	v_cvt_pk_bf16_f32 v227, v184, v185
	s_nop 1
	v_permlane16_swap_b32_e32 v224, v226
	v_permlane16_swap_b32_e32 v225, v227
	global_store_dwordx4 v214, v[224:227], s[68:69]
	s_nop 1
	v_pk_mul_f32 v[186:187], v[186:187], v[232:233] op_sel_hi:[1,0]
	v_pk_mul_f32 v[188:189], v[188:189], v[232:233] op_sel_hi:[1,0]
	v_lshlrev_b32_e32 v220, 16, v166
	v_and_b32_e32 v221, 0xffff0000, v166
	v_lshlrev_b32_e32 v222, 16, v167
	v_and_b32_e32 v223, 0xffff0000, v167
	v_pk_mul_f32 v[186:187], v[50:51], v[186:187]
	v_pk_mul_f32 v[188:189], v[52:53], v[188:189]
	v_pk_mul_f32 v[186:187], v[186:187], v[220:221]
	v_pk_mul_f32 v[188:189], v[188:189], v[222:223]
	v_cvt_pk_bf16_f32 v224, v186, v187
	v_cvt_pk_bf16_f32 v225, v188, v189
	v_pk_mul_f32 v[190:191], v[190:191], v[232:233] op_sel_hi:[1,0]
	v_pk_mul_f32 v[192:193], v[192:193], v[232:233] op_sel_hi:[1,0]
	v_lshlrev_b32_e32 v220, 16, v168
	v_and_b32_e32 v221, 0xffff0000, v168
	v_lshlrev_b32_e32 v222, 16, v169
	v_and_b32_e32 v223, 0xffff0000, v169
	v_pk_mul_f32 v[190:191], v[66:67], v[190:191]
	v_pk_mul_f32 v[192:193], v[68:69], v[192:193]
	v_pk_mul_f32 v[190:191], v[190:191], v[220:221]
	v_pk_mul_f32 v[192:193], v[192:193], v[222:223]
	v_cvt_pk_bf16_f32 v226, v190, v191
	v_cvt_pk_bf16_f32 v227, v192, v193
	s_nop 1
	v_permlane16_swap_b32_e32 v224, v226
	v_permlane16_swap_b32_e32 v225, v227
	global_store_dwordx4 v214, v[224:227], s[68:69] offset:64
	s_nop 1
	v_pk_mul_f32 v[194:195], v[194:195], v[232:233] op_sel_hi:[1,0]
	v_pk_mul_f32 v[196:197], v[196:197], v[232:233] op_sel_hi:[1,0]
	v_lshlrev_b32_e32 v220, 16, v170
	v_and_b32_e32 v221, 0xffff0000, v170
	v_lshlrev_b32_e32 v222, 16, v171
	v_and_b32_e32 v223, 0xffff0000, v171
	v_pk_mul_f32 v[194:195], v[82:83], v[194:195]
	v_pk_mul_f32 v[196:197], v[84:85], v[196:197]
	v_pk_mul_f32 v[194:195], v[194:195], v[220:221]
	v_pk_mul_f32 v[196:197], v[196:197], v[222:223]
	v_cvt_pk_bf16_f32 v224, v194, v195
	v_cvt_pk_bf16_f32 v225, v196, v197
	v_pk_mul_f32 v[198:199], v[198:199], v[232:233] op_sel_hi:[1,0]
	v_pk_mul_f32 v[200:201], v[200:201], v[232:233] op_sel_hi:[1,0]
	v_lshlrev_b32_e32 v220, 16, v172
	v_and_b32_e32 v221, 0xffff0000, v172
	v_lshlrev_b32_e32 v222, 16, v173
	v_and_b32_e32 v223, 0xffff0000, v173
	v_pk_mul_f32 v[198:199], v[98:99], v[198:199]
	v_pk_mul_f32 v[200:201], v[100:101], v[200:201]
	v_pk_mul_f32 v[198:199], v[198:199], v[220:221]
	v_pk_mul_f32 v[200:201], v[200:201], v[222:223]
	v_cvt_pk_bf16_f32 v226, v198, v199
	v_cvt_pk_bf16_f32 v227, v200, v201
	s_nop 1
	v_permlane16_swap_b32_e32 v224, v226
	v_permlane16_swap_b32_e32 v225, v227
	global_store_dwordx4 v214, v[224:227], s[68:69] offset:128
	s_nop 1
	v_pk_mul_f32 v[202:203], v[202:203], v[232:233] op_sel_hi:[1,0]
	v_pk_mul_f32 v[204:205], v[204:205], v[232:233] op_sel_hi:[1,0]
	v_lshlrev_b32_e32 v220, 16, v174
	v_and_b32_e32 v221, 0xffff0000, v174
	v_lshlrev_b32_e32 v222, 16, v175
	v_and_b32_e32 v223, 0xffff0000, v175
	v_pk_mul_f32 v[202:203], v[114:115], v[202:203]
	v_pk_mul_f32 v[204:205], v[116:117], v[204:205]
	v_pk_mul_f32 v[202:203], v[202:203], v[220:221]
	v_pk_mul_f32 v[204:205], v[204:205], v[222:223]
	v_cvt_pk_bf16_f32 v224, v202, v203
	v_cvt_pk_bf16_f32 v225, v204, v205
	v_pk_mul_f32 v[206:207], v[206:207], v[232:233] op_sel_hi:[1,0]
	v_pk_mul_f32 v[208:209], v[208:209], v[232:233] op_sel_hi:[1,0]
	v_lshlrev_b32_e32 v220, 16, v176
	v_and_b32_e32 v221, 0xffff0000, v176
	v_lshlrev_b32_e32 v222, 16, v177
	v_and_b32_e32 v223, 0xffff0000, v177
	v_pk_mul_f32 v[206:207], v[130:131], v[206:207]
	v_pk_mul_f32 v[208:209], v[132:133], v[208:209]
	v_pk_mul_f32 v[206:207], v[206:207], v[220:221]
	v_pk_mul_f32 v[208:209], v[208:209], v[222:223]
	v_cvt_pk_bf16_f32 v226, v206, v207
	v_cvt_pk_bf16_f32 v227, v208, v209
	s_nop 1
	v_permlane16_swap_b32_e32 v224, v226
	v_permlane16_swap_b32_e32 v225, v227
	global_store_dwordx4 v214, v[224:227], s[68:69] offset:192
	s_nop 1
	s_mov_b64 s[68:69], s[70:71]
	s_cmp_lt_i32 s4, 0
	s_cbranch_scc0 .Lp4n_item
